# prompt attention QK^T: K-fragment ds_reads issued two MFMAs ahead into fresh buffers, counted lgkmcnt (on top of v37)
# speedup vs baseline: 1.0093x; 1.0031x over previous
.LBB0_812:
	s_or_b64 exec, exec, s[52:53]
	s_ashr_i32 s49, s48, 31
	s_lshl_b64 s[48:49], s[48:49], 2
	s_add_u32 s48, s3, s48
	s_addc_u32 s49, s82, s49
	s_waitcnt lgkmcnt(0)
	s_barrier
	global_load_dword v149, v195, s[48:49]
	ds_read_b128 v[178:181], v142
	ds_read_b128 v[182:185], v142 offset:32
	ds_read_b128 v[186:189], v142 offset:64
	s_waitcnt lgkmcnt(2)
	v_mfma_f32_32x32x16_bf16 v[66:81], v[178:181], v[34:37], 0
	v_lshl_add_u64 v[126:127], s[50:51], 1, v[118:119]
	s_and_b64 s[48:49], vcc, s[12:13]
	s_and_b64 s[50:51], vcc, s[14:15]
	s_and_b64 s[52:53], vcc, s[16:17]
	s_and_b64 s[54:55], vcc, s[18:19]
	s_and_b64 s[56:57], vcc, s[20:21]
	ds_read_b128 v[190:193], v142 offset:96
	s_waitcnt lgkmcnt(2)
	v_mfma_f32_32x32x16_bf16 v[66:81], v[182:185], v[106:109], v[66:81]
	s_and_b64 s[58:59], vcc, s[22:23]
	s_and_b64 s[60:61], vcc, s[24:25]
	s_and_b64 s[62:63], vcc, s[26:27]
	s_and_b64 s[64:65], vcc, s[28:29]
	s_and_b64 s[66:67], vcc, s[30:31]
	s_and_b64 s[68:69], vcc, s[34:35]
	s_and_b64 s[70:71], vcc, s[36:37]
	ds_read_b128 v[178:181], v143
	s_waitcnt lgkmcnt(2)
	v_mfma_f32_32x32x16_bf16 v[66:81], v[186:189], v[102:105], v[66:81]
	s_and_b64 s[72:73], vcc, s[38:39]
	s_and_b64 s[74:75], vcc, s[42:43]
	s_and_b64 s[76:77], vcc, s[44:45]
	s_and_b64 s[78:79], vcc, s[0:1]
	s_or_b32 s80, s80, s96
	s_cmp_eq_u32 s80, 0
	ds_read_b128 v[182:185], v143 offset:32
	s_waitcnt lgkmcnt(2)
	v_mfma_f32_32x32x16_bf16 v[66:81], v[190:193], v[98:101], v[66:81]
	s_cselect_b64 s[80:81], -1, 0
	s_mov_b32 s94, 0x3fb8aa3b
	v_or_b32_e32 v152, s97, v150
	s_add_i32 s2, s2, s86
	s_cmpk_lt_i32 s2, 0x200
	s_nop 4
	s_nop 0
	s_nop 0
	v_cndmask_b32_e64 v67, v245, v67, s[50:51]
	ds_read_b128 v[186:189], v143 offset:64
	s_waitcnt lgkmcnt(2)
	v_mfma_f32_32x32x16_bf16 v[50:65], v[178:181], v[34:37], 0
	v_cndmask_b32_e64 v68, v245, v68, s[52:53]
	v_cndmask_b32_e64 v69, v245, v69, s[54:55]
	v_cndmask_b32_e64 v70, v245, v70, s[56:57]
	v_cndmask_b32_e64 v71, v245, v71, s[58:59]
	v_cndmask_b32_e64 v72, v245, v72, s[60:61]
	v_cndmask_b32_e64 v75, v245, v75, s[66:67]
	ds_read_b128 v[190:193], v143 offset:96
	s_waitcnt lgkmcnt(2)
	v_mfma_f32_32x32x16_bf16 v[50:65], v[182:185], v[106:109], v[50:65]
	v_cndmask_b32_e64 v78, v245, v78, s[72:73]
	v_cndmask_b32_e64 v79, v245, v79, s[74:75]
	v_cndmask_b32_e64 v80, v245, v80, s[76:77]
	v_cndmask_b32_e64 v81, v245, v81, s[78:79]
	s_waitcnt vmcnt(0)
	v_mul_f32_e32 v151, 0x3fb8aa3b, v149
	ds_read_b128 v[178:181], v144
	s_waitcnt lgkmcnt(2)
	v_mfma_f32_32x32x16_bf16 v[50:65], v[186:189], v[102:105], v[50:65]
	ds_read_b128 v[182:185], v144 offset:32
	s_waitcnt lgkmcnt(2)
	v_mfma_f32_32x32x16_bf16 v[50:65], v[190:193], v[98:101], v[50:65]
	ds_read_b128 v[186:189], v144 offset:64
	s_waitcnt lgkmcnt(2)
	v_mfma_f32_32x32x16_bf16 v[18:33], v[178:181], v[34:37], 0
	s_nop 6
	s_nop 1
	v_cndmask_b32_e32 v50, v245, v50, vcc
	v_cndmask_b32_e32 v54, v245, v54, vcc
	v_cndmask_b32_e32 v59, v245, v59, vcc
	v_cndmask_b32_e32 v60, v245, v60, vcc
	v_cndmask_b32_e32 v153, v245, v61, vcc
	v_cndmask_b32_e32 v63, v245, v63, vcc
	ds_read_b128 v[190:193], v144 offset:96
	s_waitcnt lgkmcnt(2)
	v_mfma_f32_32x32x16_bf16 v[18:33], v[182:185], v[106:109], v[18:33]
	v_cndmask_b32_e32 v65, v245, v65, vcc
	ds_read_b128 v[178:181], v145
	s_waitcnt lgkmcnt(2)
	v_mfma_f32_32x32x16_bf16 v[18:33], v[186:189], v[102:105], v[18:33]
	ds_read_b128 v[182:185], v145 offset:32
	s_waitcnt lgkmcnt(2)
	v_mfma_f32_32x32x16_bf16 v[18:33], v[190:193], v[98:101], v[18:33]
	ds_read_b128 v[186:189], v145 offset:64
	s_waitcnt lgkmcnt(2)
	v_mfma_f32_32x32x16_bf16 v[2:17], v[178:181], v[34:37], 0
	s_nop 7
	s_nop 0
	v_cndmask_b32_e64 v158, v20, v245, s[80:81]
	v_cndmask_b32_e64 v159, v21, v245, s[80:81]
	v_cndmask_b32_e64 v160, v22, v245, s[80:81]
	v_cndmask_b32_e64 v161, v23, v245, s[80:81]
	v_cndmask_b32_e64 v162, v24, v245, s[80:81]
	v_cndmask_b32_e64 v163, v25, v245, s[80:81]
	v_cndmask_b32_e64 v164, v26, v245, s[80:81]
	ds_read_b128 v[190:193], v145 offset:96
	s_waitcnt lgkmcnt(2)
	v_mfma_f32_32x32x16_bf16 v[2:17], v[182:185], v[106:109], v[2:17]
	v_cndmask_b32_e64 v165, v27, v245, s[80:81]
	v_cndmask_b32_e64 v166, v28, v245, s[80:81]
	v_cndmask_b32_e64 v167, v29, v245, s[80:81]
	v_cndmask_b32_e64 v168, v30, v245, s[80:81]
	ds_read_b128 v[178:181], v146
	s_waitcnt lgkmcnt(2)
	v_mfma_f32_32x32x16_bf16 v[2:17], v[186:189], v[102:105], v[2:17]
	ds_read_b128 v[182:185], v146 offset:32
	s_waitcnt lgkmcnt(2)
	v_mfma_f32_32x32x16_bf16 v[2:17], v[190:193], v[98:101], v[2:17]
	ds_read_b128 v[186:189], v146 offset:64
	s_waitcnt lgkmcnt(2)
	v_mfma_f32_32x32x16_bf16 v[34:49], v[178:181], v[34:37], 0
	s_nop 7
	s_nop 0
	v_cndmask_b32_e64 v61, v5, v245, s[80:81]
	v_cndmask_b32_e64 v30, v14, v245, s[80:81]
	v_cndmask_b32_e64 v29, v15, v245, s[80:81]
	v_cndmask_b32_e64 v28, v16, v245, s[80:81]
	v_cndmask_b32_e64 v27, v17, v245, s[80:81]
	ds_read_b128 v[190:193], v146 offset:96
	s_waitcnt lgkmcnt(2)
	v_mfma_f32_32x32x16_bf16 v[34:49], v[182:185], v[106:109], v[34:49]
	v_cndmask_b32_e32 v154, v245, v62, vcc
	v_cndmask_b32_e32 v155, v245, v64, vcc
	v_cndmask_b32_e64 v156, v18, v245, s[80:81]
	v_cndmask_b32_e64 v157, v19, v245, s[80:81]
	v_cndmask_b32_e64 v64, v4, v245, s[80:81]
	s_waitcnt lgkmcnt(1)
	v_mfma_f32_32x32x16_bf16 v[34:49], v[186:189], v[102:105], v[34:49]
	v_cndmask_b32_e32 v106, v245, v55, vcc
	v_cndmask_b32_e32 v107, v245, v56, vcc
	v_cndmask_b32_e32 v108, v245, v57, vcc
	v_cndmask_b32_e32 v109, v245, v58, vcc
	v_cndmask_b32_e64 v58, v6, v245, s[80:81]
	v_cndmask_b32_e64 v57, v7, v245, s[80:81]
	s_waitcnt lgkmcnt(0)
	v_mfma_f32_32x32x16_bf16 v[34:49], v[190:193], v[98:101], v[34:49]
	v_cndmask_b32_e64 v98, v245, v66, s[48:49]
	v_max3_f32 v66, v151, v98, v67
	v_max3_f32 v66, v66, v68, v69
	v_max3_f32 v66, v66, v70, v71
	v_cndmask_b32_e64 v99, v245, v73, s[62:63]
	v_max3_f32 v66, v66, v72, v99
	v_cndmask_b32_e64 v100, v245, v74, s[64:65]
	v_max3_f32 v66, v66, v100, v75
	v_cndmask_b32_e64 v101, v245, v76, s[68:69]
	v_cndmask_b32_e64 v102, v245, v77, s[70:71]
	v_max3_f32 v66, v66, v101, v102
	v_max3_f32 v66, v66, v78, v79
	v_max3_f32 v66, v66, v80, v81
	v_cndmask_b32_e32 v103, v245, v51, vcc
	v_max3_f32 v51, v66, v50, v103
	v_cndmask_b32_e32 v104, v245, v52, vcc
	v_cndmask_b32_e32 v105, v245, v53, vcc
	v_max3_f32 v51, v51, v104, v105
	v_max3_f32 v51, v51, v54, v106
	v_max3_f32 v51, v51, v107, v108
	v_max3_f32 v51, v51, v109, v59
	v_max3_f32 v51, v51, v60, v153
	v_max3_f32 v51, v51, v154, v63
	v_max3_f32 v51, v51, v155, v65
	v_max3_f32 v18, v51, v156, v157
	v_max3_f32 v18, v18, v158, v159
	v_max3_f32 v18, v18, v160, v161
	v_max3_f32 v18, v18, v162, v163
	v_max3_f32 v18, v18, v164, v165
	v_max3_f32 v18, v18, v166, v167
	v_cndmask_b32_e64 v77, v31, v245, s[80:81]
	v_max3_f32 v18, v18, v168, v77
	v_cndmask_b32_e64 v76, v32, v245, s[80:81]
	v_cndmask_b32_e64 v74, v33, v245, s[80:81]
	v_max3_f32 v18, v18, v76, v74
	v_cndmask_b32_e64 v73, v2, v245, s[80:81]
	v_cndmask_b32_e64 v66, v3, v245, s[80:81]
	v_max3_f32 v2, v18, v73, v66
	v_max3_f32 v2, v2, v64, v61
	v_max3_f32 v2, v2, v58, v57
	v_cndmask_b32_e64 v55, v8, v245, s[80:81]
	v_cndmask_b32_e64 v53, v9, v245, s[80:81]
	v_max3_f32 v2, v2, v55, v53
	v_cndmask_b32_e64 v52, v10, v245, s[80:81]
	v_cndmask_b32_e64 v33, v11, v245, s[80:81]
	v_max3_f32 v2, v2, v52, v33
	v_cndmask_b32_e64 v32, v12, v245, s[80:81]
	v_cndmask_b32_e64 v31, v13, v245, s[80:81]
	v_max3_f32 v2, v2, v32, v31
	v_max3_f32 v2, v2, v30, v29
	v_max3_f32 v2, v2, v28, v27
	v_cndmask_b32_e64 v26, v34, v245, s[12:13]
	v_cndmask_b32_e64 v25, v245, v35, s[46:47]
	v_max3_f32 v2, v2, v26, v25
	v_cndmask_b32_e64 v24, v36, v245, s[16:17]
	v_cndmask_b32_e64 v23, v37, v245, s[18:19]
	v_max3_f32 v2, v2, v24, v23
	v_cndmask_b32_e64 v22, v38, v245, s[20:21]
	v_cndmask_b32_e64 v21, v39, v245, s[22:23]
	v_max3_f32 v2, v2, v22, v21
	v_cndmask_b32_e64 v20, v40, v245, s[24:25]
	v_cndmask_b32_e64 v19, v41, v245, s[26:27]
	v_max3_f32 v2, v2, v20, v19
	v_cndmask_b32_e64 v18, v42, v245, s[28:29]
	v_cndmask_b32_e64 v17, v43, v245, s[30:31]
	v_max3_f32 v2, v2, v18, v17
	v_cndmask_b32_e64 v16, v44, v245, s[34:35]
	v_cndmask_b32_e64 v15, v45, v245, s[36:37]
	v_max3_f32 v2, v2, v16, v15
	v_cndmask_b32_e64 v14, v46, v245, s[38:39]
	v_cndmask_b32_e64 v13, v47, v245, s[42:43]
	v_max3_f32 v2, v2, v14, v13
	v_cndmask_b32_e64 v12, v48, v245, s[44:45]
	v_cndmask_b32_e64 v11, v49, v245, s[0:1]
	v_max3_f32 v2, v2, v12, v11
	v_mov_b32_e32 v3, v2
	v_mov_b32_e32 v206, v2
	s_nop 1
	v_permlane32_swap_b32 v3, v206
	v_max_f32_e32 v10, v3, v206
	v_sub_f32_e32 v2, v98, v10
	v_exp_f32_e32 v2, v2
	v_sub_f32_e32 v3, v67, v10
	v_exp_f32_e32 v3, v3
	v_sub_f32_e32 v35, v100, v10
	v_add_f32_e32 v4, 0, v2
	v_exp_f32_e32 v35, v35
	v_add_f32_e32 v5, v3, v4
	v_sub_f32_e32 v4, v68, v10
	v_exp_f32_e32 v4, v4
	v_sub_f32_e32 v36, v75, v10
	v_exp_f32_e32 v36, v36
	v_sub_f32_e32 v37, v101, v10
	v_add_f32_e32 v6, v4, v5
	v_sub_f32_e32 v5, v69, v10
	v_exp_f32_e32 v5, v5
	v_exp_f32_e32 v38, v37
	v_sub_f32_e32 v37, v102, v10
	v_exp_f32_e32 v39, v37
	v_add_f32_e32 v7, v5, v6
	v_sub_f32_e32 v6, v70, v10
	v_exp_f32_e32 v6, v6
	v_sub_f32_e32 v37, v78, v10
	v_exp_f32_e32 v40, v37
	v_sub_f32_e32 v37, v79, v10
	v_add_f32_e32 v8, v6, v7
	v_sub_f32_e32 v7, v71, v10
	v_exp_f32_e32 v7, v7
	v_exp_f32_e32 v45, v37
	v_sub_f32_e32 v37, v80, v10
	v_exp_f32_e32 v48, v37
	v_add_f32_e32 v9, v7, v8
	v_sub_f32_e32 v8, v72, v10
	v_exp_f32_e32 v8, v8
	v_sub_f32_e32 v37, v81, v10
	v_exp_f32_e32 v51, v37
	v_sub_f32_e32 v37, v50, v10
	v_add_f32_e32 v34, v8, v9
	v_sub_f32_e32 v9, v99, v10
	v_exp_f32_e32 v9, v9
	v_exp_f32_e32 v37, v37
	v_sub_f32_e32 v41, v103, v10
	v_exp_f32_e32 v41, v41
	v_add_f32_e32 v34, v9, v34
	v_add_f32_e32 v34, v35, v34
	v_add_f32_e32 v34, v36, v34
	v_add_f32_e32 v34, v38, v34
	v_add_f32_e32 v34, v39, v34
	v_add_f32_e32 v34, v40, v34
	v_add_f32_e32 v34, v45, v34
	v_sub_f32_e32 v42, v104, v10
	v_add_f32_e32 v34, v48, v34
	v_exp_f32_e32 v43, v42
	v_sub_f32_e32 v42, v105, v10
	v_add_f32_e32 v34, v51, v34
	v_exp_f32_e32 v44, v42
	v_sub_f32_e32 v42, v54, v10
	v_add_f32_e32 v34, v37, v34
	v_exp_f32_e32 v47, v42
	v_sub_f32_e32 v42, v106, v10
	v_add_f32_e32 v34, v41, v34
	v_exp_f32_e32 v56, v42
	v_sub_f32_e32 v42, v107, v10
	v_add_f32_e32 v34, v43, v34
	v_exp_f32_e32 v62, v42
	v_sub_f32_e32 v42, v108, v10
	v_add_f32_e32 v34, v44, v34
	v_exp_f32_e32 v67, v42
	v_sub_f32_e32 v42, v109, v10
	v_add_f32_e32 v34, v47, v34
	v_exp_f32_e32 v42, v42
	v_sub_f32_e32 v46, v59, v10
	v_add_f32_e32 v34, v56, v34
	v_exp_f32_e32 v46, v46
	v_sub_f32_e32 v49, v60, v10
	v_add_f32_e32 v34, v62, v34
	v_exp_f32_e32 v50, v49
	v_sub_f32_e32 v49, v153, v10
	v_add_f32_e32 v34, v67, v34
	v_exp_f32_e32 v54, v49
	v_sub_f32_e32 v49, v154, v10
	v_add_f32_e32 v34, v42, v34
	v_exp_f32_e32 v59, v49
	v_sub_f32_e32 v49, v63, v10
	v_add_f32_e32 v34, v46, v34
	v_exp_f32_e32 v69, v49
	v_sub_f32_e32 v49, v155, v10
	v_add_f32_e32 v34, v50, v34
	v_exp_f32_e32 v72, v49
	v_sub_f32_e32 v49, v65, v10
	v_add_f32_e32 v34, v54, v34
	v_exp_f32_e32 v78, v49
	v_sub_f32_e32 v49, v156, v10
	v_add_f32_e32 v34, v59, v34
	v_exp_f32_e32 v49, v49
	v_sub_f32_e32 v60, v157, v10
	v_add_f32_e32 v34, v69, v34
	v_exp_f32_e32 v60, v60
	v_sub_f32_e32 v63, v158, v10
	v_add_f32_e32 v34, v72, v34
	v_exp_f32_e32 v65, v63
	v_sub_f32_e32 v63, v159, v10
	v_add_f32_e32 v34, v78, v34
	v_exp_f32_e32 v68, v63
	v_sub_f32_e32 v63, v160, v10
	v_add_f32_e32 v34, v49, v34
	v_exp_f32_e32 v71, v63
	v_sub_f32_e32 v63, v161, v10
	v_add_f32_e32 v34, v60, v34
	v_exp_f32_e32 v98, v63
	v_sub_f32_e32 v63, v162, v10
	v_add_f32_e32 v34, v65, v34
	v_exp_f32_e32 v103, v63
	v_sub_f32_e32 v63, v163, v10
	v_add_f32_e32 v34, v68, v34
	v_exp_f32_e32 v104, v63
	v_sub_f32_e32 v63, v164, v10
	v_add_f32_e32 v34, v71, v34
	v_exp_f32_e32 v63, v63
	v_sub_f32_e32 v70, v165, v10
	v_add_f32_e32 v34, v98, v34
	v_exp_f32_e32 v70, v70
	v_sub_f32_e32 v75, v166, v10
	v_add_f32_e32 v34, v103, v34
	v_exp_f32_e32 v75, v75
	v_sub_f32_e32 v79, v167, v10
	v_add_f32_e32 v34, v104, v34
	v_exp_f32_e32 v80, v79
	v_sub_f32_e32 v79, v168, v10
	v_add_f32_e32 v34, v63, v34
	v_exp_f32_e32 v101, v79
	v_sub_f32_e32 v77, v77, v10
	v_add_f32_e32 v34, v70, v34
	v_exp_f32_e32 v155, v77
	v_sub_f32_e32 v76, v76, v10
	v_add_f32_e32 v34, v75, v34
	v_exp_f32_e32 v159, v76
	v_sub_f32_e32 v74, v74, v10
	v_add_f32_e32 v34, v80, v34
	v_exp_f32_e32 v163, v74
	v_sub_f32_e32 v73, v73, v10
	v_add_f32_e32 v34, v101, v34
	v_exp_f32_e32 v74, v73
	v_sub_f32_e32 v66, v66, v10
	v_add_f32_e32 v34, v155, v34
	v_exp_f32_e32 v102, v66
	v_sub_f32_e32 v64, v64, v10
	v_add_f32_e32 v34, v159, v34
	v_exp_f32_e32 v153, v64
	v_sub_f32_e32 v61, v61, v10
	v_add_f32_e32 v34, v163, v34
	v_exp_f32_e32 v154, v61
	v_sub_f32_e32 v58, v58, v10
	v_add_f32_e32 v34, v74, v34
	v_exp_f32_e32 v157, v58
	v_sub_f32_e32 v57, v57, v10
	v_add_f32_e32 v34, v102, v34
	v_exp_f32_e32 v166, v57
	v_sub_f32_e32 v55, v55, v10
	v_add_f32_e32 v34, v153, v34
	v_exp_f32_e32 v167, v55
	v_sub_f32_e32 v53, v53, v10
	v_add_f32_e32 v34, v154, v34
	v_exp_f32_e32 v168, v53
	v_sub_f32_e32 v52, v52, v10
	v_add_f32_e32 v34, v157, v34
	v_exp_f32_e32 v109, v52
	v_sub_f32_e32 v33, v33, v10
	v_add_f32_e32 v34, v166, v34
	v_exp_f32_e32 v156, v33
	v_sub_f32_e32 v32, v32, v10
	v_add_f32_e32 v34, v167, v34
	v_exp_f32_e32 v158, v32
	v_sub_f32_e32 v31, v31, v10
	v_add_f32_e32 v34, v168, v34
	v_exp_f32_e32 v160, v31
	v_sub_f32_e32 v30, v30, v10
	v_add_f32_e32 v34, v109, v34
	v_exp_f32_e32 v161, v30
	v_sub_f32_e32 v29, v29, v10
	v_add_f32_e32 v33, v156, v34
	v_exp_f32_e32 v162, v29
	v_sub_f32_e32 v28, v28, v10
	v_add_f32_e32 v32, v158, v33
	v_exp_f32_e32 v164, v28
	v_sub_f32_e32 v27, v27, v10
	v_add_f32_e32 v31, v160, v32
	v_exp_f32_e32 v165, v27
	v_sub_f32_e32 v26, v26, v10
	v_add_f32_e32 v30, v161, v31
	v_exp_f32_e32 v73, v26
	v_sub_f32_e32 v25, v25, v10
	v_add_f32_e32 v29, v162, v30
	v_exp_f32_e32 v76, v25
	v_sub_f32_e32 v24, v24, v10
	v_add_f32_e32 v28, v164, v29
	v_exp_f32_e32 v77, v24
	v_sub_f32_e32 v23, v23, v10
	v_add_f32_e32 v27, v165, v28
	v_exp_f32_e32 v79, v23
	v_sub_f32_e32 v22, v22, v10
	v_add_f32_e32 v26, v73, v27
	v_exp_f32_e32 v81, v22
	v_sub_f32_e32 v21, v21, v10
	v_add_f32_e32 v25, v76, v26
	v_exp_f32_e32 v99, v21
	v_sub_f32_e32 v20, v20, v10
	v_add_f32_e32 v24, v77, v25
	v_exp_f32_e32 v100, v20
	v_sub_f32_e32 v19, v19, v10
	v_add_u32_e32 v105, v130, v131
	v_add_f32_e32 v23, v79, v24
	v_exp_f32_e32 v108, v19
	v_sub_f32_e32 v18, v18, v10
	v_cvt_pk_bf16_f32 v2, v2, v3
	v_cvt_pk_bf16_f32 v3, v4, v5
	v_cvt_pk_bf16_f32 v4, v6, v7
	v_cvt_pk_bf16_f32 v5, v8, v9
	ds_read_b128 v[6:9], v105 offset:36864
	v_add_f32_e32 v22, v81, v23
	v_exp_f32_e32 v52, v18
	v_sub_f32_e32 v17, v17, v10
	v_add_f32_e32 v21, v99, v22
	v_exp_f32_e32 v53, v17
	v_sub_f32_e32 v16, v16, v10
	v_add_f32_e32 v20, v100, v21
	v_exp_f32_e32 v55, v16
	v_sub_f32_e32 v15, v15, v10
	v_add_f32_e32 v19, v108, v20
	v_exp_f32_e32 v57, v15
	v_sub_f32_e32 v14, v14, v10
	v_add_f32_e32 v18, v52, v19
	v_exp_f32_e32 v58, v14
	v_sub_f32_e32 v13, v13, v10
	v_add_f32_e32 v17, v53, v18
	v_exp_f32_e32 v61, v13
	v_sub_f32_e32 v12, v12, v10
	v_add_f32_e32 v16, v55, v17
	v_exp_f32_e32 v64, v12
	v_sub_f32_e32 v11, v11, v10
	v_add_f32_e32 v15, v57, v16
	v_exp_f32_e32 v66, v11
	v_add_u32_e32 v106, v130, v132
	v_add_f32_e32 v14, v58, v15
	s_waitcnt lgkmcnt(0)
	v_mfma_f32_32x32x16_bf16 v[18:33], v[6:9], v[2:5], 0
	ds_read_b128 v[6:9], v106 offset:36864
	v_cvt_pk_bf16_f32 v170, v35, v36
	v_cvt_pk_bf16_f32 v171, v38, v39
	v_cvt_pk_bf16_f32 v172, v40, v45
	v_cvt_pk_bf16_f32 v173, v48, v51
	ds_read_b128 v[174:177], v105 offset:36896
	v_add_f32_e32 v13, v61, v14
	v_add_f32_e32 v12, v64, v13
	v_add_f32_e32 v11, v66, v12
	ds_bpermute_b32 v12, v129, v11
	v_fma_f32 v10, v149, s94, -v10
	v_exp_f32_e32 v10, v10
	s_waitcnt lgkmcnt(1)
	v_mfma_f32_32x32x16_bf16 v[18:33], v[174:177], v[170:173], v[18:33]
	s_waitcnt lgkmcnt(0)
	v_add_f32_e32 v11, v11, v12
	ds_read_b128 v[174:177], v106 offset:36896
	v_add_f32_e32 v34, v10, v11
	v_add_u32_e32 v107, v133, v131
	v_cvt_pk_bf16_f32 v36, v37, v41
	v_cvt_pk_bf16_f32 v37, v43, v44
	v_cvt_pk_bf16_f32 v38, v47, v56
	v_mfma_f32_32x32x16_bf16 v[2:17], v[6:9], v[2:5], 0
	v_cvt_pk_bf16_f32 v39, v62, v67
	v_add_u32_e32 v106, v133, v132
	v_add_u32_e32 v105, v134, v131
	v_div_scale_f32 v35, vcc, v34, v34, 1.0
	s_waitcnt lgkmcnt(0)
	v_mfma_f32_32x32x16_bf16 v[2:17], v[174:177], v[170:173], v[2:17]
	ds_read_b128 v[178:181], v107 offset:36864
	ds_read_b128 v[182:185], v106 offset:36864
	ds_read_b128 v[186:189], v107 offset:36896
	s_waitcnt lgkmcnt(2)
	v_mfma_f32_32x32x16_bf16 v[18:33], v[178:181], v[36:39], v[18:33]
	ds_read_b128 v[190:193], v106 offset:36896
	s_waitcnt lgkmcnt(2)
	v_mfma_f32_32x32x16_bf16 v[2:17], v[182:185], v[36:39], v[2:17]
	v_cvt_pk_bf16_f32 v36, v42, v46
	v_cvt_pk_bf16_f32 v37, v50, v54
	v_cvt_pk_bf16_f32 v38, v59, v69
	v_cvt_pk_bf16_f32 v39, v72, v78
	ds_read_b128 v[178:181], v105 offset:36864
	s_waitcnt lgkmcnt(2)
	v_mfma_f32_32x32x16_bf16 v[18:33], v[186:189], v[36:39], v[18:33]
	v_add_u32_e32 v194, v134, v132
	ds_read_b128 v[182:185], v194 offset:36864
	s_waitcnt lgkmcnt(2)
	v_mfma_f32_32x32x16_bf16 v[2:17], v[190:193], v[36:39], v[2:17]
	v_cvt_pk_bf16_f32 v36, v49, v60
	v_cvt_pk_bf16_f32 v37, v65, v68
	v_cvt_pk_bf16_f32 v38, v71, v98
	v_cvt_pk_bf16_f32 v39, v103, v104
	v_add_u32_e32 v104, v134, v132
	v_add_u32_e32 v103, v135, v131
	ds_read_b128 v[186:189], v105 offset:36896
	s_waitcnt lgkmcnt(2)
	v_mfma_f32_32x32x16_bf16 v[18:33], v[178:181], v[36:39], v[18:33]
	v_or_b32_e32 v98, s88, v152
	ds_read_b128 v[190:193], v104 offset:36896
	s_waitcnt lgkmcnt(2)
	v_mfma_f32_32x32x16_bf16 v[2:17], v[182:185], v[36:39], v[2:17]
	v_cvt_pk_bf16_f32 v36, v63, v70
	v_cvt_pk_bf16_f32 v37, v75, v80
	v_cvt_pk_bf16_f32 v38, v101, v155
	v_cvt_pk_bf16_f32 v39, v159, v163
	v_add_u32_e32 v101, v136, v131
	ds_read_b128 v[178:181], v103 offset:36864
	s_waitcnt lgkmcnt(2)
	v_mfma_f32_32x32x16_bf16 v[18:33], v[186:189], v[36:39], v[18:33]
	v_add_u32_e32 v202, v135, v132
	ds_read_b128 v[182:185], v202 offset:36864
	s_waitcnt lgkmcnt(2)
	v_mfma_f32_32x32x16_bf16 v[2:17], v[190:193], v[36:39], v[2:17]
	v_cvt_pk_bf16_f32 v36, v74, v102
	v_cvt_pk_bf16_f32 v37, v153, v154
	v_cvt_pk_bf16_f32 v38, v157, v166
	v_cvt_pk_bf16_f32 v39, v167, v168
	v_add_u32_e32 v102, v135, v132
	ds_read_b128 v[186:189], v103 offset:36896
	s_waitcnt lgkmcnt(2)
	v_mfma_f32_32x32x16_bf16 v[18:33], v[178:181], v[36:39], v[18:33]
	ds_read_b128 v[190:193], v102 offset:36896
	s_waitcnt lgkmcnt(2)
	v_mfma_f32_32x32x16_bf16 v[2:17], v[182:185], v[36:39], v[2:17]
	v_cvt_pk_bf16_f32 v36, v109, v156
	v_cvt_pk_bf16_f32 v37, v158, v160
	v_cvt_pk_bf16_f32 v38, v161, v162
	v_cvt_pk_bf16_f32 v39, v164, v165
	ds_read_b128 v[178:181], v101 offset:36864
	s_waitcnt lgkmcnt(2)
	v_mfma_f32_32x32x16_bf16 v[18:33], v[186:189], v[36:39], v[18:33]
	v_add_u32_e32 v203, v136, v132
	ds_read_b128 v[182:185], v203 offset:36864
	s_waitcnt lgkmcnt(2)
	v_mfma_f32_32x32x16_bf16 v[2:17], v[190:193], v[36:39], v[2:17]
	v_cvt_pk_bf16_f32 v36, v73, v76
	v_cvt_pk_bf16_f32 v37, v77, v79
	v_cvt_pk_bf16_f32 v38, v81, v99
	v_cvt_pk_bf16_f32 v39, v100, v108
	v_add_u32_e32 v100, v136, v132
	v_mov_b32_e32 v99, s89
	ds_read_b128 v[186:189], v101 offset:36896
	s_waitcnt lgkmcnt(2)
	v_mfma_f32_32x32x16_bf16 v[18:33], v[178:181], v[36:39], v[18:33]
	ds_read_b128 v[190:193], v100 offset:36896
	s_waitcnt lgkmcnt(2)
	v_mfma_f32_32x32x16_bf16 v[2:17], v[182:185], v[36:39], v[2:17]
	v_cvt_pk_bf16_f32 v36, v52, v53
	v_cvt_pk_bf16_f32 v37, v55, v57
	v_cvt_pk_bf16_f32 v38, v58, v61
	v_cvt_pk_bf16_f32 v39, v64, v66
	s_waitcnt lgkmcnt(1)
	v_mfma_f32_32x32x16_bf16 v[18:33], v[186:189], v[36:39], v[18:33]
	s_waitcnt lgkmcnt(0)
	v_mfma_f32_32x32x16_bf16 v[2:17], v[190:193], v[36:39], v[2:17]
	v_rcp_f32_e32 v36, v35
	s_nop 0
	v_fma_f32 v37, -v35, v36, 1.0
	v_fmac_f32_e32 v36, v37, v36
	v_div_scale_f32 v37, vcc, 1.0, v34, 1.0
	v_mul_f32_e32 v38, v37, v36
	v_fma_f32 v39, -v35, v38, v37
	v_fmac_f32_e32 v38, v39, v36
	v_fma_f32 v35, -v35, v38, v37
	v_div_fmas_f32 v35, v35, v36, v38
	v_div_fixup_f32 v36, v35, v34, 1.0
	v_lshlrev_b64 v[34:35], 11, v[98:99]
	v_bfe_u32 v204, v0, 5, 1
	v_lshl_add_u64 v[34:35], v[126:127], 0, v[34:35]
	v_lshlrev_b32_e32 v204, 3, v204
	v_mov_b32_e32 v205, 0
	v_mul_f32_e32 v18, v18, v36
	v_mul_f32_e32 v19, v19, v36
	v_cvt_pk_bf16_f32 v18, v18, v19
	v_mul_f32_e32 v19, v20, v36
	v_mul_f32_e32 v20, v21, v36
	v_cvt_pk_bf16_f32 v19, v19, v20
	v_mul_f32_e32 v20, v22, v36
	v_mul_f32_e32 v21, v23, v36
	v_cvt_pk_bf16_f32 v20, v20, v21
	v_mul_f32_e32 v21, v24, v36
	v_mul_f32_e32 v22, v25, v36
	v_cvt_pk_bf16_f32 v21, v21, v22
	v_lshl_add_u64 v[34:35], v[34:35], 0, v[204:205]
	v_mul_f32_e32 v26, v26, v36
	v_mul_f32_e32 v27, v27, v36
	v_cvt_pk_bf16_f32 v26, v26, v27
	v_mul_f32_e32 v27, v28, v36
	v_mul_f32_e32 v28, v29, v36
	v_cvt_pk_bf16_f32 v27, v27, v28
	v_mul_f32_e32 v28, v30, v36
	v_mul_f32_e32 v29, v31, v36
	v_cvt_pk_bf16_f32 v28, v28, v29
	v_mul_f32_e32 v29, v32, v36
	v_mul_f32_e32 v30, v33, v36
	v_cvt_pk_bf16_f32 v29, v29, v30
	v_permlane32_swap_b32 v18, v20
	v_permlane32_swap_b32 v19, v21
	global_store_dwordx4 v[34:35], v[18:21], off
	v_permlane32_swap_b32 v26, v28
	v_permlane32_swap_b32 v27, v29
	global_store_dwordx4 v[34:35], v[26:29], off offset:32
	v_mul_f32_e32 v2, v2, v36
	v_mul_f32_e32 v3, v3, v36
	v_cvt_pk_bf16_f32 v2, v2, v3
	v_mul_f32_e32 v3, v4, v36
	v_mul_f32_e32 v4, v5, v36
	v_cvt_pk_bf16_f32 v3, v3, v4
	v_mul_f32_e32 v4, v6, v36
	v_mul_f32_e32 v5, v7, v36
	v_cvt_pk_bf16_f32 v4, v4, v5
	v_mul_f32_e32 v5, v8, v36
	v_mul_f32_e32 v6, v9, v36
	v_cvt_pk_bf16_f32 v5, v5, v6
	v_mul_f32_e32 v10, v10, v36
	v_mul_f32_e32 v11, v11, v36
	v_cvt_pk_bf16_f32 v10, v10, v11
	v_mul_f32_e32 v11, v12, v36
	v_mul_f32_e32 v12, v13, v36
	v_cvt_pk_bf16_f32 v11, v11, v12
	v_mul_f32_e32 v12, v14, v36
	v_mul_f32_e32 v13, v15, v36
	v_cvt_pk_bf16_f32 v12, v12, v13
	v_mul_f32_e32 v13, v16, v36
	v_mul_f32_e32 v14, v17, v36
	v_cvt_pk_bf16_f32 v13, v13, v14
	v_permlane32_swap_b32 v2, v4
	v_permlane32_swap_b32 v3, v5
	global_store_dwordx4 v[34:35], v[2:5], off offset:64
	v_permlane32_swap_b32 v10, v12
	v_permlane32_swap_b32 v11, v13
	global_store_dwordx4 v[34:35], v[10:13], off offset:96
	ds_read_b128 v[178:181], v143
	ds_read_b128 v[182:185], v143 offset:32
	ds_read_b128 v[186:189], v143 offset:64
	s_waitcnt lgkmcnt(2)
	v_mfma_f32_32x32x16_bf16 v[66:81], v[178:181], v[94:97], 0
	v_or_b32_e32 v98, s87, v150
	v_or_b32_e32 v98, s88, v98
	ds_read_b128 v[190:193], v143 offset:96
	s_waitcnt lgkmcnt(2)
	v_mfma_f32_32x32x16_bf16 v[66:81], v[182:185], v[90:93], v[66:81]
	ds_read_b128 v[178:181], v144
	s_waitcnt lgkmcnt(2)
	v_mfma_f32_32x32x16_bf16 v[66:81], v[186:189], v[86:89], v[66:81]
	ds_read_b128 v[182:185], v144 offset:32
	s_waitcnt lgkmcnt(2)
	v_mfma_f32_32x32x16_bf16 v[66:81], v[190:193], v[82:85], v[66:81]
	ds_read_b128 v[186:189], v144 offset:64
	s_waitcnt lgkmcnt(2)
	v_mfma_f32_32x32x16_bf16 v[34:49], v[178:181], v[94:97], 0
	s_nop 6
	s_nop 0
	s_nop 0
	v_cndmask_b32_e64 v66, v245, v66, s[48:49]
	v_cndmask_b32_e64 v68, v245, v68, s[52:53]
	v_cndmask_b32_e64 v69, v245, v69, s[54:55]
	v_cndmask_b32_e64 v70, v245, v70, s[56:57]
	v_cndmask_b32_e64 v71, v245, v71, s[58:59]
	v_cndmask_b32_e64 v72, v245, v72, s[60:61]
	ds_read_b128 v[190:193], v144 offset:96
	s_waitcnt lgkmcnt(2)
	v_mfma_f32_32x32x16_bf16 v[34:49], v[182:185], v[90:93], v[34:49]
	v_cndmask_b32_e64 v73, v245, v73, s[62:63]
	v_cndmask_b32_e64 v74, v245, v74, s[64:65]
	v_cndmask_b32_e64 v75, v245, v75, s[66:67]
	v_cndmask_b32_e64 v76, v245, v76, s[68:69]
	v_cndmask_b32_e64 v77, v245, v77, s[70:71]
	v_cndmask_b32_e64 v78, v245, v78, s[72:73]
	v_cndmask_b32_e64 v79, v245, v79, s[74:75]
	ds_read_b128 v[178:181], v145
	s_waitcnt lgkmcnt(2)
	v_mfma_f32_32x32x16_bf16 v[34:49], v[186:189], v[86:89], v[34:49]
	v_cndmask_b32_e64 v80, v245, v80, s[76:77]
	v_cndmask_b32_e64 v81, v245, v81, s[78:79]
	ds_read_b128 v[182:185], v145 offset:32
	s_waitcnt lgkmcnt(2)
	v_mfma_f32_32x32x16_bf16 v[34:49], v[190:193], v[82:85], v[34:49]
	ds_read_b128 v[186:189], v145 offset:64
	s_waitcnt lgkmcnt(2)
	v_mfma_f32_32x32x16_bf16 v[18:33], v[178:181], v[94:97], 0
	s_nop 6
	s_nop 1
	v_cndmask_b32_e64 v42, v42, v245, s[80:81]
	ds_read_b128 v[190:193], v145 offset:96
	s_waitcnt lgkmcnt(2)
	v_mfma_f32_32x32x16_bf16 v[18:33], v[182:185], v[90:93], v[18:33]
	ds_read_b128 v[178:181], v146
	s_waitcnt lgkmcnt(2)
	v_mfma_f32_32x32x16_bf16 v[18:33], v[186:189], v[86:89], v[18:33]
	ds_read_b128 v[182:185], v146 offset:32
	s_waitcnt lgkmcnt(2)
	v_mfma_f32_32x32x16_bf16 v[18:33], v[190:193], v[82:85], v[18:33]
	ds_read_b128 v[186:189], v146 offset:64
	s_waitcnt lgkmcnt(2)
	v_mfma_f32_32x32x16_bf16 v[2:17], v[178:181], v[94:97], 0
	s_nop 7
	s_nop 0
	v_cndmask_b32_e64 v108, v18, v245, s[80:81]
	v_cndmask_b32_e64 v109, v19, v245, s[80:81]
	v_cndmask_b32_e64 v150, v20, v245, s[80:81]
	v_cndmask_b32_e64 v156, v26, v245, s[80:81]
	v_cndmask_b32_e64 v157, v27, v245, s[80:81]
	v_cndmask_b32_e64 v158, v28, v245, s[80:81]
	v_cndmask_b32_e64 v159, v29, v245, s[80:81]
	ds_read_b128 v[190:193], v146 offset:96
	s_waitcnt lgkmcnt(2)
	v_mfma_f32_32x32x16_bf16 v[2:17], v[182:185], v[90:93], v[2:17]
	v_cndmask_b32_e64 v160, v30, v245, s[80:81]
	v_cndmask_b32_e64 v161, v31, v245, s[80:81]
	v_cndmask_b32_e64 v162, v32, v245, s[80:81]
	v_cndmask_b32_e64 v163, v33, v245, s[80:81]
	ds_read_b128 v[178:181], v147
	s_waitcnt lgkmcnt(2)
	v_mfma_f32_32x32x16_bf16 v[2:17], v[186:189], v[86:89], v[2:17]
	ds_read_b128 v[182:185], v147 offset:32
	s_waitcnt lgkmcnt(2)
	v_mfma_f32_32x32x16_bf16 v[2:17], v[190:193], v[82:85], v[2:17]
	ds_read_b128 v[186:189], v147 offset:64
	s_waitcnt lgkmcnt(2)
	v_mfma_f32_32x32x16_bf16 v[50:65], v[178:181], v[94:97], 0
	v_cndmask_b32_e64 v94, v46, v245, s[80:81]
	v_cndmask_b32_e64 v95, v47, v245, s[80:81]
	v_cndmask_b32_e64 v96, v48, v245, s[80:81]
	v_cndmask_b32_e64 v97, v49, v245, s[80:81]
	ds_read_b128 v[190:193], v147 offset:96
	s_waitcnt lgkmcnt(2)
	v_mfma_f32_32x32x16_bf16 v[50:65], v[182:185], v[90:93], v[50:65]
	v_cndmask_b32_e64 v152, v22, v245, s[80:81]
	v_cndmask_b32_e64 v153, v23, v245, s[80:81]
	v_cndmask_b32_e64 v154, v24, v245, s[80:81]
	v_cndmask_b32_e64 v155, v25, v245, s[80:81]
	s_waitcnt lgkmcnt(1)
	v_mfma_f32_32x32x16_bf16 v[50:65], v[186:189], v[86:89], v[50:65]
	v_cndmask_b32_e64 v90, v41, v245, s[80:81]
	v_cndmask_b32_e64 v91, v43, v245, s[80:81]
	v_cndmask_b32_e64 v92, v44, v245, s[80:81]
	v_cndmask_b32_e64 v93, v45, v245, s[80:81]
	s_waitcnt lgkmcnt(0)
	v_mfma_f32_32x32x16_bf16 v[50:65], v[190:193], v[82:85], v[50:65]
	v_cndmask_b32_e64 v82, v245, v67, s[50:51]
	v_max3_f32 v67, v151, v66, v82
	v_max3_f32 v67, v67, v68, v69
	v_max3_f32 v67, v67, v70, v71
	v_max3_f32 v67, v67, v72, v73
	v_max3_f32 v67, v67, v74, v75
	v_max3_f32 v67, v67, v76, v77
	v_max3_f32 v67, v67, v78, v79
	v_max3_f32 v67, v67, v80, v81
	v_cndmask_b32_e64 v83, v34, v245, s[80:81]
	v_cndmask_b32_e64 v84, v35, v245, s[80:81]
	v_max3_f32 v34, v67, v83, v84
	v_cndmask_b32_e64 v85, v36, v245, s[80:81]
	v_cndmask_b32_e64 v86, v37, v245, s[80:81]
	v_max3_f32 v34, v34, v85, v86
	v_cndmask_b32_e64 v87, v38, v245, s[80:81]
	v_cndmask_b32_e64 v88, v39, v245, s[80:81]
	v_max3_f32 v34, v34, v87, v88
	v_cndmask_b32_e64 v89, v40, v245, s[80:81]
	v_max3_f32 v34, v34, v89, v90
	v_max3_f32 v34, v34, v42, v91
	v_max3_f32 v34, v34, v92, v93
	v_max3_f32 v34, v34, v94, v95
	v_max3_f32 v34, v34, v96, v97
	v_max3_f32 v18, v34, v108, v109
	v_cndmask_b32_e64 v151, v21, v245, s[80:81]
	v_max3_f32 v18, v18, v150, v151
	v_max3_f32 v18, v18, v152, v153
	v_max3_f32 v18, v18, v154, v155
	v_max3_f32 v18, v18, v156, v157
	v_max3_f32 v18, v18, v158, v159
	v_max3_f32 v18, v18, v160, v161
	v_max3_f32 v18, v18, v162, v163
	v_max3_f32 v18, v18, v2, v3
	v_max3_f32 v18, v18, v4, v5
	v_max3_f32 v18, v18, v6, v7
	v_max3_f32 v18, v18, v8, v9
	v_max3_f32 v18, v18, v10, v11
	v_max3_f32 v18, v18, v12, v13
	v_max3_f32 v18, v18, v14, v15
	v_max3_f32 v18, v18, v16, v17
	v_cndmask_b32_e64 v67, v50, v245, s[12:13]
	v_cndmask_b32_e64 v50, v245, v51, s[46:47]
	v_max3_f32 v18, v18, v67, v50
	v_cndmask_b32_e64 v49, v52, v245, s[16:17]
	v_cndmask_b32_e64 v48, v53, v245, s[18:19]
	v_max3_f32 v18, v18, v49, v48
	v_cndmask_b32_e64 v47, v54, v245, s[20:21]
	v_cndmask_b32_e64 v45, v55, v245, s[22:23]
	v_max3_f32 v18, v18, v47, v45
	v_cndmask_b32_e64 v43, v56, v245, s[24:25]
	v_cndmask_b32_e64 v40, v57, v245, s[26:27]
	v_max3_f32 v18, v18, v43, v40
	v_cndmask_b32_e64 v34, v58, v245, s[28:29]
	v_cndmask_b32_e64 v33, v59, v245, s[30:31]
	v_max3_f32 v18, v18, v34, v33
	v_cndmask_b32_e64 v32, v60, v245, s[34:35]
	v_cndmask_b32_e64 v31, v61, v245, s[36:37]
	v_max3_f32 v18, v18, v32, v31
	v_cndmask_b32_e64 v30, v62, v245, s[38:39]
	v_cndmask_b32_e64 v29, v63, v245, s[42:43]
	v_max3_f32 v18, v18, v30, v29
	v_cndmask_b32_e64 v28, v64, v245, s[44:45]
	v_cndmask_b32_e64 v27, v65, v245, s[0:1]
	v_max3_f32 v18, v18, v28, v27
	v_mov_b32_e32 v19, v18
	v_mov_b32_e32 v206, v18
	s_nop 1
	v_permlane32_swap_b32 v19, v206
	v_max_f32_e32 v26, v19, v206
	v_sub_f32_e32 v18, v66, v26
	v_exp_f32_e32 v18, v18
	v_sub_f32_e32 v19, v82, v26
	v_exp_f32_e32 v19, v19
	v_sub_f32_e32 v38, v76, v26
	v_add_f32_e32 v20, 0, v18
	v_exp_f32_e32 v38, v38
	v_add_f32_e32 v21, v19, v20
	v_sub_f32_e32 v20, v68, v26
	v_exp_f32_e32 v20, v20
	v_sub_f32_e32 v39, v77, v26
	v_exp_f32_e32 v39, v39
	v_sub_f32_e32 v41, v78, v26
	v_add_f32_e32 v22, v20, v21
	v_sub_f32_e32 v21, v69, v26
	v_exp_f32_e32 v21, v21
	v_exp_f32_e32 v44, v41
	v_sub_f32_e32 v41, v79, v26
	v_exp_f32_e32 v54, v41
	v_add_f32_e32 v23, v21, v22
	v_sub_f32_e32 v22, v70, v26
	v_exp_f32_e32 v22, v22
	v_sub_f32_e32 v41, v80, v26
	v_exp_f32_e32 v58, v41
	v_sub_f32_e32 v41, v81, v26
	v_add_f32_e32 v24, v22, v23
	v_sub_f32_e32 v23, v71, v26
	v_exp_f32_e32 v23, v23
	v_exp_f32_e32 v60, v41
	v_sub_f32_e32 v53, v87, v26
	v_exp_f32_e32 v56, v53
	v_add_f32_e32 v25, v23, v24
	v_sub_f32_e32 v24, v72, v26
	v_exp_f32_e32 v24, v24
	v_sub_f32_e32 v53, v88, v26
	v_exp_f32_e32 v63, v53
	v_sub_f32_e32 v53, v89, v26
	v_add_f32_e32 v35, v24, v25
	v_sub_f32_e32 v25, v73, v26
	v_exp_f32_e32 v25, v25
	v_exp_f32_e32 v70, v53
	v_sub_f32_e32 v53, v90, v26
	v_sub_f32_e32 v42, v42, v26
	v_add_f32_e32 v36, v25, v35
	v_sub_f32_e32 v35, v74, v26
	v_exp_f32_e32 v35, v35
	v_exp_f32_e32 v42, v42
	v_sub_f32_e32 v55, v92, v26
	v_exp_f32_e32 v57, v55
	v_add_f32_e32 v37, v35, v36
	v_sub_f32_e32 v36, v75, v26
	v_exp_f32_e32 v36, v36
	v_exp_f32_e32 v75, v53
	v_sub_f32_e32 v53, v91, v26
	v_exp_f32_e32 v53, v53
	v_add_f32_e32 v37, v36, v37
	v_add_f32_e32 v37, v38, v37
	v_add_f32_e32 v37, v39, v37
	v_add_f32_e32 v37, v44, v37
	v_add_f32_e32 v37, v54, v37
	v_add_f32_e32 v37, v58, v37
	v_add_f32_e32 v41, v60, v37
	v_sub_f32_e32 v37, v83, v26
	v_exp_f32_e32 v37, v37
	v_sub_f32_e32 v55, v93, v26
	v_exp_f32_e32 v59, v55
	v_sub_f32_e32 v55, v94, v26
	v_add_f32_e32 v46, v37, v41
	v_sub_f32_e32 v41, v84, v26
	v_exp_f32_e32 v41, v41
	v_exp_f32_e32 v66, v55
	v_sub_f32_e32 v55, v95, v26
	v_exp_f32_e32 v78, v55
	v_add_f32_e32 v51, v41, v46
	v_sub_f32_e32 v46, v85, v26
	v_exp_f32_e32 v46, v46
	v_sub_f32_e32 v55, v96, v26
	v_exp_f32_e32 v82, v55
	v_sub_f32_e32 v55, v97, v26
	v_add_f32_e32 v52, v46, v51
	v_sub_f32_e32 v51, v86, v26
	v_exp_f32_e32 v51, v51
	v_exp_f32_e32 v85, v55
	v_sub_f32_e32 v55, v108, v26
	v_exp_f32_e32 v55, v55
	v_add_f32_e32 v52, v51, v52
	v_add_f32_e32 v52, v56, v52
	v_add_f32_e32 v52, v63, v52
	v_add_f32_e32 v52, v70, v52
	v_add_f32_e32 v52, v75, v52
	v_add_f32_e32 v52, v42, v52
	v_add_f32_e32 v52, v53, v52
	v_add_f32_e32 v52, v57, v52
	v_add_f32_e32 v52, v59, v52
	v_add_f32_e32 v52, v66, v52
	v_sub_f32_e32 v61, v109, v26
	v_add_f32_e32 v52, v78, v52
	v_exp_f32_e32 v62, v61
	v_sub_f32_e32 v61, v150, v26
	v_add_f32_e32 v52, v82, v52
	v_exp_f32_e32 v68, v61
	v_sub_f32_e32 v61, v151, v26
	v_add_f32_e32 v52, v85, v52
	v_exp_f32_e32 v74, v61
	v_sub_f32_e32 v61, v152, v26
	v_add_f32_e32 v52, v55, v52
	v_exp_f32_e32 v80, v61
	v_sub_f32_e32 v61, v153, v26
	v_add_f32_e32 v52, v62, v52
	v_exp_f32_e32 v88, v61
	v_sub_f32_e32 v61, v154, v26
	v_add_f32_e32 v52, v68, v52
	v_exp_f32_e32 v94, v61
	v_sub_f32_e32 v61, v155, v26
	v_add_f32_e32 v52, v74, v52
	v_exp_f32_e32 v109, v61
	v_sub_f32_e32 v61, v156, v26
	v_add_f32_e32 v52, v80, v52
	v_exp_f32_e32 v64, v61
	v_sub_f32_e32 v61, v157, v26
	v_add_f32_e32 v52, v88, v52
	v_exp_f32_e32 v77, v61
	v_sub_f32_e32 v61, v158, v26
	v_add_f32_e32 v52, v94, v52
	v_exp_f32_e32 v81, v61
	v_sub_f32_e32 v61, v159, v26
	v_add_f32_e32 v52, v109, v52
	v_exp_f32_e32 v83, v61
	v_sub_f32_e32 v61, v160, v26
	v_add_f32_e32 v52, v64, v52
	v_exp_f32_e32 v90, v61
	v_sub_f32_e32 v61, v161, v26
	v_add_f32_e32 v52, v77, v52
	v_exp_f32_e32 v150, v61
	v_sub_f32_e32 v61, v162, v26
	v_add_f32_e32 v52, v81, v52
	v_exp_f32_e32 v152, v61
	v_sub_f32_e32 v61, v163, v26
	v_add_f32_e32 v52, v83, v52
	v_exp_f32_e32 v153, v61
	v_sub_f32_e32 v2, v2, v26
	v_add_f32_e32 v52, v90, v52
	v_exp_f32_e32 v79, v2
	v_sub_f32_e32 v3, v3, v26
	v_add_f32_e32 v52, v150, v52
	v_exp_f32_e32 v86, v3
	v_sub_f32_e32 v3, v4, v26
	v_add_f32_e32 v52, v152, v52
	v_exp_f32_e32 v92, v3
	v_sub_f32_e32 v3, v5, v26
	v_add_f32_e32 v52, v153, v52
	v_exp_f32_e32 v97, v3
	v_sub_f32_e32 v3, v6, v26
	v_add_f32_e32 v2, v79, v52
	v_exp_f32_e32 v151, v3
	v_sub_f32_e32 v3, v7, v26
	v_add_f32_e32 v2, v86, v2
	v_exp_f32_e32 v154, v3
	v_sub_f32_e32 v3, v8, v26
	v_add_f32_e32 v2, v92, v2
	v_exp_f32_e32 v155, v3
	v_sub_f32_e32 v3, v9, v26
	v_add_f32_e32 v2, v97, v2
	v_exp_f32_e32 v156, v3
	v_sub_f32_e32 v3, v10, v26
	v_add_f32_e32 v2, v151, v2
	v_exp_f32_e32 v84, v3
	v_sub_f32_e32 v3, v11, v26
	v_add_f32_e32 v2, v154, v2
	v_exp_f32_e32 v87, v3
	v_sub_f32_e32 v3, v12, v26
	v_add_f32_e32 v2, v155, v2
	v_exp_f32_e32 v89, v3
	v_sub_f32_e32 v3, v13, v26
	v_add_f32_e32 v2, v156, v2
	v_exp_f32_e32 v91, v3
	v_sub_f32_e32 v3, v14, v26
	v_add_f32_e32 v2, v84, v2
	v_exp_f32_e32 v93, v3
	v_sub_f32_e32 v3, v15, v26
	v_add_f32_e32 v2, v87, v2
	v_exp_f32_e32 v95, v3
	v_sub_f32_e32 v3, v16, v26
	v_add_f32_e32 v2, v89, v2
	v_exp_f32_e32 v96, v3
	v_sub_f32_e32 v3, v17, v26
	v_add_f32_e32 v2, v91, v2
	v_exp_f32_e32 v108, v3
	v_sub_f32_e32 v3, v67, v26
	v_add_f32_e32 v2, v93, v2
	v_exp_f32_e32 v61, v3
	v_sub_f32_e32 v3, v50, v26
	v_add_f32_e32 v2, v95, v2
	v_exp_f32_e32 v65, v3
	v_sub_f32_e32 v3, v49, v26
	v_add_f32_e32 v2, v96, v2
	v_exp_f32_e32 v67, v3
	v_sub_f32_e32 v3, v48, v26
	v_add_f32_e32 v2, v108, v2
	v_exp_f32_e32 v69, v3
	v_sub_f32_e32 v3, v47, v26
	v_add_f32_e32 v2, v61, v2
	v_exp_f32_e32 v71, v3
	v_sub_f32_e32 v3, v45, v26
	v_add_f32_e32 v2, v65, v2
	v_exp_f32_e32 v72, v3
	v_sub_f32_e32 v3, v43, v26
	v_add_f32_e32 v2, v67, v2
	v_exp_f32_e32 v73, v3
	v_sub_f32_e32 v3, v40, v26
	v_add_f32_e32 v2, v69, v2
	v_exp_f32_e32 v76, v3
	v_sub_f32_e32 v3, v34, v26
	v_add_f32_e32 v2, v71, v2
	v_exp_f32_e32 v40, v3
	v_sub_f32_e32 v3, v33, v26
	v_add_f32_e32 v2, v72, v2
	v_exp_f32_e32 v43, v3
	v_sub_f32_e32 v3, v32, v26
	v_add_f32_e32 v2, v73, v2
	v_exp_f32_e32 v45, v3
	v_sub_f32_e32 v3, v31, v26
	v_add_f32_e32 v2, v76, v2
	v_exp_f32_e32 v47, v3
	v_sub_f32_e32 v3, v30, v26
	v_add_f32_e32 v2, v40, v2
	v_exp_f32_e32 v48, v3
	v_sub_f32_e32 v3, v29, v26
	v_add_f32_e32 v2, v43, v2
	v_exp_f32_e32 v49, v3
	v_sub_f32_e32 v3, v28, v26
	v_add_f32_e32 v2, v45, v2
	v_exp_f32_e32 v50, v3
	v_sub_f32_e32 v3, v27, v26
	v_add_f32_e32 v2, v47, v2
	v_exp_f32_e32 v52, v3
	v_add_f32_e32 v2, v48, v2
	v_add_f32_e32 v2, v49, v2
	v_add_f32_e32 v2, v50, v2
	v_add_f32_e32 v2, v52, v2
	v_mov_b32_e32 v3, v2
	v_mov_b32_e32 v206, v2
	s_nop 1
	v_permlane32_swap_b32 v3, v206
	v_add_f32_e32 v2, v3, v206
	v_fma_f32 v3, v149, s94, -v26
	v_exp_f32_e32 v3, v3
	s_nop 0
	v_add_f32_e32 v34, v3, v2
	v_cvt_pk_bf16_f32 v2, v18, v19
	v_cvt_pk_bf16_f32 v3, v20, v21
	v_cvt_pk_bf16_f32 v4, v22, v23
	v_cvt_pk_bf16_f32 v5, v24, v25
	ds_read_b128 v[6:9], v107 offset:36864
	s_waitcnt lgkmcnt(0)
	v_mfma_f32_32x32x16_bf16 v[18:33], v[6:9], v[2:5], 0
	ds_read_b128 v[6:9], v106 offset:36864
	v_cvt_pk_bf16_f32 v158, v35, v36
	v_cvt_pk_bf16_f32 v159, v38, v39
	v_cvt_pk_bf16_f32 v160, v44, v54
	v_cvt_pk_bf16_f32 v161, v58, v60
	ds_read_b128 v[162:165], v107 offset:36896
	v_add_u32_e32 v35, v137, v131
	s_waitcnt lgkmcnt(0)
	v_mfma_f32_32x32x16_bf16 v[18:33], v[162:165], v[158:161], v[18:33]
	ds_read_b128 v[162:165], v106 offset:36896
	v_cvt_pk_bf16_f32 v36, v37, v41
	v_cvt_pk_bf16_f32 v37, v46, v51
	v_cvt_pk_bf16_f32 v38, v56, v63
	v_cvt_pk_bf16_f32 v39, v70, v75
	v_add_u32_e32 v44, v137, v132
	v_mfma_f32_32x32x16_bf16 v[2:17], v[6:9], v[2:5], 0
	s_waitcnt lgkmcnt(0)
	v_mfma_f32_32x32x16_bf16 v[2:17], v[162:165], v[158:161], v[2:17]
	ds_read_b128 v[178:181], v105 offset:36864
	ds_read_b128 v[182:185], v104 offset:36864
	ds_read_b128 v[186:189], v105 offset:36896
	s_waitcnt lgkmcnt(2)
	v_mfma_f32_32x32x16_bf16 v[18:33], v[178:181], v[36:39], v[18:33]
	ds_read_b128 v[190:193], v104 offset:36896
	s_waitcnt lgkmcnt(2)
	v_mfma_f32_32x32x16_bf16 v[2:17], v[182:185], v[36:39], v[2:17]
	v_cvt_pk_bf16_f32 v36, v42, v53
	v_cvt_pk_bf16_f32 v37, v57, v59
	v_cvt_pk_bf16_f32 v38, v66, v78
	v_cvt_pk_bf16_f32 v39, v82, v85
	ds_read_b128 v[178:181], v103 offset:36864
	s_waitcnt lgkmcnt(2)
	v_mfma_f32_32x32x16_bf16 v[18:33], v[186:189], v[36:39], v[18:33]
	ds_read_b128 v[182:185], v102 offset:36864
	s_waitcnt lgkmcnt(2)
	v_mfma_f32_32x32x16_bf16 v[2:17], v[190:193], v[36:39], v[2:17]
	v_cvt_pk_bf16_f32 v36, v55, v62
	v_cvt_pk_bf16_f32 v37, v68, v74
	v_cvt_pk_bf16_f32 v38, v80, v88
	v_cvt_pk_bf16_f32 v39, v94, v109
	ds_read_b128 v[186:189], v103 offset:36896
	s_waitcnt lgkmcnt(2)
	v_mfma_f32_32x32x16_bf16 v[18:33], v[178:181], v[36:39], v[18:33]
	ds_read_b128 v[190:193], v102 offset:36896
	s_waitcnt lgkmcnt(2)
	v_mfma_f32_32x32x16_bf16 v[2:17], v[182:185], v[36:39], v[2:17]
	v_cvt_pk_bf16_f32 v36, v64, v77
	v_cvt_pk_bf16_f32 v37, v81, v83
	v_cvt_pk_bf16_f32 v38, v90, v150
	v_cvt_pk_bf16_f32 v39, v152, v153
	ds_read_b128 v[178:181], v101 offset:36864
	s_waitcnt lgkmcnt(2)
	v_mfma_f32_32x32x16_bf16 v[18:33], v[186:189], v[36:39], v[18:33]
	ds_read_b128 v[182:185], v100 offset:36864
	s_waitcnt lgkmcnt(2)
	v_mfma_f32_32x32x16_bf16 v[2:17], v[190:193], v[36:39], v[2:17]
	v_cvt_pk_bf16_f32 v36, v79, v86
	v_cvt_pk_bf16_f32 v37, v92, v97
	v_cvt_pk_bf16_f32 v38, v151, v154
	v_cvt_pk_bf16_f32 v39, v155, v156
	ds_read_b128 v[186:189], v101 offset:36896
	s_waitcnt lgkmcnt(2)
	v_mfma_f32_32x32x16_bf16 v[18:33], v[178:181], v[36:39], v[18:33]
	ds_read_b128 v[190:193], v100 offset:36896
	s_waitcnt lgkmcnt(2)
	v_mfma_f32_32x32x16_bf16 v[2:17], v[182:185], v[36:39], v[2:17]
	v_cvt_pk_bf16_f32 v36, v84, v87
	v_cvt_pk_bf16_f32 v37, v89, v91
	v_cvt_pk_bf16_f32 v38, v93, v95
	v_cvt_pk_bf16_f32 v39, v96, v108
	ds_read_b128 v[178:181], v35 offset:36864
	s_waitcnt lgkmcnt(2)
	v_mfma_f32_32x32x16_bf16 v[18:33], v[186:189], v[36:39], v[18:33]
	ds_read_b128 v[182:185], v44 offset:36864
	s_waitcnt lgkmcnt(2)
	v_mfma_f32_32x32x16_bf16 v[2:17], v[190:193], v[36:39], v[2:17]
	v_cvt_pk_bf16_f32 v36, v61, v65
	v_cvt_pk_bf16_f32 v37, v67, v69
	v_cvt_pk_bf16_f32 v38, v71, v72
	v_cvt_pk_bf16_f32 v39, v73, v76
	ds_read_b128 v[186:189], v35 offset:36896
	s_waitcnt lgkmcnt(2)
	v_mfma_f32_32x32x16_bf16 v[18:33], v[178:181], v[36:39], v[18:33]
	ds_read_b128 v[190:193], v44 offset:36896
	s_waitcnt lgkmcnt(2)
	v_mfma_f32_32x32x16_bf16 v[2:17], v[182:185], v[36:39], v[2:17]
	v_cvt_pk_bf16_f32 v36, v40, v43
	v_cvt_pk_bf16_f32 v37, v45, v47
	v_cvt_pk_bf16_f32 v38, v48, v49
	v_cvt_pk_bf16_f32 v39, v50, v52
	v_div_scale_f32 v35, s[48:49], v34, v34, 1.0
	s_waitcnt lgkmcnt(1)
	v_mfma_f32_32x32x16_bf16 v[18:33], v[186:189], v[36:39], v[18:33]
	s_waitcnt lgkmcnt(0)
	v_mfma_f32_32x32x16_bf16 v[2:17], v[190:193], v[36:39], v[2:17]
	v_rcp_f32_e32 v36, v35
	s_nop 0
	v_fma_f32 v37, -v35, v36, 1.0
	v_fmac_f32_e32 v36, v37, v36
	v_div_scale_f32 v37, vcc, 1.0, v34, 1.0
	v_mul_f32_e32 v38, v37, v36
	v_fma_f32 v39, -v35, v38, v37
	v_fmac_f32_e32 v38, v39, v36
	v_fma_f32 v35, -v35, v38, v37
	v_div_fmas_f32 v35, v35, v36, v38
	v_div_fixup_f32 v36, v35, v34, 1.0
	v_lshlrev_b64 v[34:35], 11, v[98:99]
	v_bfe_u32 v204, v0, 5, 1
	v_lshl_add_u64 v[34:35], v[126:127], 0, v[34:35]
	v_lshlrev_b32_e32 v204, 3, v204
	v_mov_b32_e32 v205, 0
	v_mul_f32_e32 v18, v18, v36
	v_mul_f32_e32 v19, v19, v36
	v_cvt_pk_bf16_f32 v18, v18, v19
	v_mul_f32_e32 v19, v20, v36
	v_mul_f32_e32 v20, v21, v36
	v_cvt_pk_bf16_f32 v19, v19, v20
	v_mul_f32_e32 v20, v22, v36
	v_mul_f32_e32 v21, v23, v36
	v_cvt_pk_bf16_f32 v20, v20, v21
	v_mul_f32_e32 v21, v24, v36
	v_mul_f32_e32 v22, v25, v36
	v_cvt_pk_bf16_f32 v21, v21, v22
	v_lshl_add_u64 v[34:35], v[34:35], 0, v[204:205]
	v_mul_f32_e32 v26, v26, v36
	v_mul_f32_e32 v27, v27, v36
	v_cvt_pk_bf16_f32 v26, v26, v27
	v_mul_f32_e32 v27, v28, v36
	v_mul_f32_e32 v28, v29, v36
	v_cvt_pk_bf16_f32 v27, v27, v28
	v_mul_f32_e32 v28, v30, v36
	v_mul_f32_e32 v29, v31, v36
	v_cvt_pk_bf16_f32 v28, v28, v29
	v_mul_f32_e32 v29, v32, v36
	v_mul_f32_e32 v30, v33, v36
	v_cvt_pk_bf16_f32 v29, v29, v30
	v_permlane32_swap_b32 v18, v20
	v_permlane32_swap_b32 v19, v21
	global_store_dwordx4 v[34:35], v[18:21], off
	v_permlane32_swap_b32 v26, v28
	v_permlane32_swap_b32 v27, v29
	global_store_dwordx4 v[34:35], v[26:29], off offset:32
	v_mul_f32_e32 v2, v2, v36
	v_mul_f32_e32 v3, v3, v36
	v_cvt_pk_bf16_f32 v2, v2, v3
	v_mul_f32_e32 v3, v4, v36
	v_mul_f32_e32 v4, v5, v36
	v_cvt_pk_bf16_f32 v3, v3, v4
	v_mul_f32_e32 v4, v6, v36
	v_mul_f32_e32 v5, v7, v36
	v_cvt_pk_bf16_f32 v4, v4, v5
	v_mul_f32_e32 v5, v8, v36
	v_mul_f32_e32 v6, v9, v36
	v_cvt_pk_bf16_f32 v5, v5, v6
	v_mul_f32_e32 v10, v10, v36
	v_mul_f32_e32 v11, v11, v36
	v_cvt_pk_bf16_f32 v10, v10, v11
	v_mul_f32_e32 v11, v12, v36
	v_mul_f32_e32 v12, v13, v36
	v_cvt_pk_bf16_f32 v11, v11, v12
	v_mul_f32_e32 v12, v14, v36
	v_mul_f32_e32 v13, v15, v36
	v_cvt_pk_bf16_f32 v12, v12, v13
	v_mul_f32_e32 v13, v16, v36
	v_mul_f32_e32 v14, v17, v36
	v_cvt_pk_bf16_f32 v13, v13, v14
	v_permlane32_swap_b32 v2, v4
	v_permlane32_swap_b32 v3, v5
	global_store_dwordx4 v[34:35], v[2:5], off offset:64
	v_permlane32_swap_b32 v10, v12
	v_permlane32_swap_b32 v11, v13
	global_store_dwordx4 v[34:35], v[10:13], off offset:96
	s_cbranch_scc0 .LBB0_821
